# step17: + work-queue prefetch atomics return directly into the next-item register (no immediate vmcnt(0)/readfirstlane at tile start)
# baseline (speedup 1.0000x reference)
.LBB0_483:
	v_mov_b32_e32 v229, 0
	s_and_saveexec_b64 s[6:7], s[0:1]
	s_cbranch_execz .LBB0_487
	s_mov_b64 s[30:31], exec
	v_mbcnt_lo_u32_b32 v2, s30, 0
	v_mbcnt_hi_u32_b32 v2, s31, v2
	v_cmp_eq_u32_e32 vcc, 0, v2
	s_and_saveexec_b64 s[26:27], vcc
	s_cbranch_execz .LBB0_486
	s_bcnt1_i32_b64 s20, s[30:31]
	v_mov_b32_e32 v3, s20
	global_atomic_add v229, v171, v3, s[24:25] sc0
.LBB0_486:
	s_or_b64 exec, exec, s[26:27]
.LBB0_487:
	s_or_b64 exec, exec, s[6:7]
	s_lshl_b32 s27, s45, 6
	s_and_b32 s26, s27, 0xffffff00
	v_add_u32_e32 v2, s26, v192
	v_ashrrev_i32_e32 v3, 31, v2
	v_cmp_gt_i32_e32 vcc, s35, v2
	v_lshlrev_b64 v[4:5], 11, v[2:3]
	v_lshl_add_u64 v[186:187], v[172:173], 0, v[4:5]
	v_cndmask_b32_e32 v3, 30, v228, vcc
	v_and_b32_e32 v3, v3, v2
	v_cmp_ne_u32_e64 s[6:7], 0, v3
	s_and_saveexec_b64 s[30:31], s[6:7]
	s_xor_b64 s[6:7], exec, s[30:31]
	s_cbranch_execnz .LBB0_495
	s_andn2_saveexec_b64 s[6:7], s[6:7]
	s_cbranch_execnz .LBB0_496

.LBB0_590:
	v_mov_b32_e32 v156, 0
	s_and_saveexec_b64 s[22:23], s[0:1]
	s_cbranch_execz .LBB0_594
	s_mov_b64 s[26:27], exec
	v_mbcnt_lo_u32_b32 v2, s26, 0
	v_mbcnt_hi_u32_b32 v2, s27, v2
	v_cmp_eq_u32_e32 vcc, 0, v2
	s_and_saveexec_b64 s[24:25], vcc
	s_cbranch_execz .LBB0_593
	s_bcnt1_i32_b64 s26, s[26:27]
	v_mov_b32_e32 v3, s26
	global_atomic_add v156, v123, v3, s[20:21] sc0
.LBB0_593:
	s_or_b64 exec, exec, s[24:25]
.LBB0_594:
	s_or_b64 exec, exec, s[22:23]
	s_add_i32 s22, s53, s52
	s_lshl_b32 s23, s22, 5
	s_and_b32 s24, s23, 0xffffff00
	s_add_i32 s24, s24, 0x8000
	v_add_u32_e32 v2, s24, v138
	v_ashrrev_i32_e32 v3, 31, v2
	v_lshlrev_b64 v[2:3], 12, v[2:3]
	v_lshl_add_u64 v[2:3], v[124:125], 0, v[2:3]
	s_lshl_b32 s22, s22, 7
	v_add_co_u32_e32 v6, vcc, s34, v2
	s_and_b32 s25, s22, 0x380
	s_nop 0
	v_addc_co_u32_e32 v7, vcc, 0, v3, vcc
	v_or_b32_e32 v4, s25, v137
	global_load_dwordx4 v[38:41], v[6:7], off offset:-4096
	global_load_dwordx4 v[42:45], v[6:7], off
	v_add_co_u32_e32 v6, vcc, s35, v2
	v_lshlrev_b32_e32 v122, 12, v4
	s_nop 0
	v_addc_co_u32_e32 v7, vcc, 0, v3, vcc
	v_lshl_add_u64 v[4:5], v[126:127], 0, v[122:123]
	global_load_dwordx4 v[46:49], v[6:7], off
	global_load_dwordx4 v[50:53], v[2:3], off
	global_load_dwordx4 v[54:57], v[4:5], off
	v_add_co_u32_e32 v2, vcc, s36, v4
	s_lshl_b32 s27, s53, 5
	s_nop 0
	v_addc_co_u32_e32 v3, vcc, 0, v5, vcc
	global_load_dwordx4 v[58:61], v[2:3], off
	s_lshl_b32 s53, s53, 7
	s_add_i32 s27, s50, s27
	s_add_i32 s53, s51, s53
	s_and_b32 s27, s27, 0xffffff00
	s_lshl_b32 s53, s53, 11
	v_add_u32_e32 v62, s27, v151
	s_and_b32 s27, s53, 0x1c0000
	v_ashrrev_i32_e32 v63, 31, v62
	v_mov_b32_e32 v2, 0
	v_lshlrev_b64 v[62:63], 12, v[62:63]
	v_add_u32_e32 v122, s27, v152
	s_mov_b32 s26, 0
	s_mov_b64 s[22:23], 0
	v_mov_b32_e32 v3, v2
	v_mov_b32_e32 v4, v2
	v_mov_b32_e32 v5, v2
	v_mov_b32_e32 v6, v2
	v_mov_b32_e32 v7, v2
	v_mov_b32_e32 v8, v2
	v_mov_b32_e32 v9, v2
	v_mov_b32_e32 v10, v2
	v_mov_b32_e32 v11, v2
	v_mov_b32_e32 v12, v2
	v_mov_b32_e32 v13, v2
	v_mov_b32_e32 v14, v2
	v_mov_b32_e32 v15, v2
	v_mov_b32_e32 v16, v2
	v_mov_b32_e32 v17, v2
	v_mov_b32_e32 v18, v2
	v_mov_b32_e32 v19, v2
	v_mov_b32_e32 v20, v2
	v_mov_b32_e32 v21, v2
	v_mov_b32_e32 v22, v2
	v_mov_b32_e32 v23, v2
	v_mov_b32_e32 v24, v2
	v_mov_b32_e32 v25, v2
	v_mov_b32_e32 v26, v2
	v_mov_b32_e32 v27, v2
	v_mov_b32_e32 v28, v2
	v_mov_b32_e32 v29, v2
	v_mov_b32_e32 v30, v2
	v_mov_b32_e32 v31, v2
	v_mov_b32_e32 v32, v2
	v_mov_b32_e32 v33, v2
	v_mov_b32_e32 v34, v2
	v_mov_b32_e32 v35, v2
	v_mov_b32_e32 v36, v2
	v_lshl_add_u64 v[62:63], v[128:129], 0, v[62:63]
	v_lshl_add_u64 v[64:65], v[122:123], 1, v[128:129]
	v_mov_b32_e32 v37, v2
	v_mov_b32_e32 v74, v2
	v_mov_b32_e32 v75, v2
	v_mov_b32_e32 v76, v2
	v_mov_b32_e32 v77, v2
	s_waitcnt vmcnt(2)
	ds_write_b128 v142, v[50:53]
	ds_write_b128 v142, v[38:41] offset:128
	ds_write_b128 v143, v[42:45]
	ds_write_b128 v144, v[46:49]
	s_waitcnt vmcnt(1)
	ds_write_b128 v141, v[54:57] offset:32768
	s_waitcnt vmcnt(0)
	ds_write_b128 v141, v[58:61] offset:40960
	v_mov_b32_e32 v38, v2
	v_mov_b32_e32 v39, v2
	v_mov_b32_e32 v40, v2
	v_mov_b32_e32 v41, v2
	v_mov_b32_e32 v42, v2
	v_mov_b32_e32 v43, v2
	v_mov_b32_e32 v44, v2
	v_mov_b32_e32 v45, v2
	v_mov_b32_e32 v46, v2
	v_mov_b32_e32 v47, v2
	v_mov_b32_e32 v48, v2
	v_mov_b32_e32 v49, v2
	v_mov_b32_e32 v50, v2
	v_mov_b32_e32 v51, v2
	v_mov_b32_e32 v52, v2
	v_mov_b32_e32 v53, v2
	v_mov_b32_e32 v54, v2
	v_mov_b32_e32 v55, v2
	v_mov_b32_e32 v56, v2
	v_mov_b32_e32 v57, v2
	v_mov_b32_e32 v58, v2
	v_mov_b32_e32 v59, v2
	v_mov_b32_e32 v60, v2
	v_mov_b32_e32 v61, v2
	s_waitcnt lgkmcnt(0)
	s_barrier

.LBB0_607:
	v_mov_b32_e32 v163, 0
	s_and_saveexec_b64 s[34:35], s[0:1]
	s_cbranch_execz .LBB0_611
	s_mov_b64 s[38:39], exec
	v_mbcnt_lo_u32_b32 v2, s38, 0
	v_mbcnt_hi_u32_b32 v2, s39, v2
	v_cmp_eq_u32_e32 vcc, 0, v2
	s_and_saveexec_b64 s[36:37], vcc
	s_cbranch_execz .LBB0_610
	s_bcnt1_i32_b64 s6, s[38:39]
	v_mov_b32_e32 v3, s6
	global_atomic_add v163, v131, v3, s[30:31] sc0
.LBB0_610:
	s_or_b64 exec, exec, s[36:37]
.LBB0_611:
	s_or_b64 exec, exec, s[34:35]
	s_lshl_b32 s6, s50, 6
	s_add_i32 s6, s6, s45
	s_and_b32 s34, s6, 0xffffff00
	v_or_b32_e32 v2, s34, v144
	s_lshl_b32 s6, s50, 8
	v_ashrrev_i32_e32 v3, 31, v2
	s_and_b32 s35, s6, 0x300
	v_lshlrev_b64 v[2:3], 12, v[2:3]
	v_readfirstlane_b32 s6, v145
	v_lshl_add_u64 v[136:137], v[132:133], 0, v[2:3]
	v_or_b32_e32 v2, s35, v144
	s_mov_b32 m0, s6
	v_readfirstlane_b32 s6, v156
	v_lshlrev_b32_e32 v130, 12, v2
	s_barrier
	global_load_lds_dwordx4 v[136:137], off
	v_lshl_add_u64 v[140:141], v[136:137], 0, s[16:17]
	s_mov_b32 m0, s6
	v_readfirstlane_b32 s6, v157
	v_lshl_add_u64 v[138:139], v[134:135], 0, v[130:131]
	global_load_lds_dwordx4 v[140:141], off
	s_mov_b32 m0, s6
	v_readfirstlane_b32 s6, v158
	global_load_lds_dwordx4 v[138:139], off
	v_lshl_add_u64 v[142:143], v[138:139], 0, s[16:17]
	s_mov_b32 m0, s6
	v_readfirstlane_b32 s6, v159
	global_load_lds_dwordx4 v[142:143], off
	v_lshl_add_u64 v[2:3], v[136:137], 0, 64
	s_mov_b32 m0, s6
	v_readfirstlane_b32 s6, v160
	global_load_lds_dwordx4 v[2:3], off
	v_lshl_add_u64 v[2:3], v[136:137], 0, s[18:19]
	s_mov_b32 m0, s6
	v_readfirstlane_b32 s6, v161
	global_load_lds_dwordx4 v[2:3], off
	v_lshl_add_u64 v[2:3], v[138:139], 0, 64
	s_mov_b32 m0, s6
	v_readfirstlane_b32 s6, v162
	global_load_lds_dwordx4 v[2:3], off
	v_lshl_add_u64 v[2:3], v[138:139], 0, s[18:19]
	s_mov_b32 m0, s6
	v_readfirstlane_b32 s6, v147
	global_load_lds_dwordx4 v[2:3], off
	v_lshl_add_u64 v[2:3], v[136:137], 0, s[20:21]
	s_mov_b32 m0, s6
	v_readfirstlane_b32 s6, v148
	global_load_lds_dwordx4 v[2:3], off
	v_lshl_add_u64 v[2:3], v[136:137], 0, s[22:23]
	s_mov_b32 m0, s6
	v_readfirstlane_b32 s6, v149
	global_load_lds_dwordx4 v[2:3], off
	v_lshl_add_u64 v[2:3], v[138:139], 0, s[20:21]
	s_mov_b32 m0, s6
	v_readfirstlane_b32 s6, v150
	global_load_lds_dwordx4 v[2:3], off
	v_lshl_add_u64 v[2:3], v[138:139], 0, s[22:23]
	s_mov_b32 m0, s6
	s_mov_b32 s37, 3
	global_load_lds_dwordx4 v[2:3], off
	v_mov_b32_e32 v2, 0
	s_mov_b32 s38, 0
	s_mov_b32 s36, 0
	v_mov_b32_e32 v3, v2
	v_mov_b32_e32 v4, v2
	v_mov_b32_e32 v5, v2
	v_mov_b32_e32 v6, v2
	v_mov_b32_e32 v7, v2
	v_mov_b32_e32 v8, v2
	v_mov_b32_e32 v9, v2
	v_mov_b32_e32 v10, v2
	v_mov_b32_e32 v11, v2
	v_mov_b32_e32 v12, v2
	v_mov_b32_e32 v13, v2
	v_mov_b32_e32 v14, v2
	v_mov_b32_e32 v15, v2
	v_mov_b32_e32 v16, v2
	v_mov_b32_e32 v17, v2
	v_mov_b32_e32 v18, v2
	v_mov_b32_e32 v19, v2
	v_mov_b32_e32 v20, v2
	v_mov_b32_e32 v21, v2
	v_mov_b32_e32 v22, v2
	v_mov_b32_e32 v23, v2
	v_mov_b32_e32 v24, v2
	v_mov_b32_e32 v25, v2
	v_mov_b32_e32 v26, v2
	v_mov_b32_e32 v27, v2
	v_mov_b32_e32 v28, v2
	v_mov_b32_e32 v29, v2
	v_mov_b32_e32 v30, v2
	v_mov_b32_e32 v31, v2
	v_mov_b32_e32 v32, v2
	v_mov_b32_e32 v33, v2
	v_mov_b32_e32 v34, v2
	v_mov_b32_e32 v35, v2
	v_mov_b32_e32 v36, v2
	v_mov_b32_e32 v37, v2
	v_mov_b32_e32 v38, v2
	v_mov_b32_e32 v39, v2
	v_mov_b32_e32 v40, v2
	v_mov_b32_e32 v41, v2
	v_mov_b32_e32 v42, v2
	v_mov_b32_e32 v43, v2
	v_mov_b32_e32 v44, v2
	v_mov_b32_e32 v45, v2
	v_mov_b32_e32 v46, v2
	v_mov_b32_e32 v47, v2
	v_mov_b32_e32 v48, v2
	v_mov_b32_e32 v49, v2
	v_mov_b32_e32 v50, v2
	v_mov_b32_e32 v51, v2
	v_mov_b32_e32 v52, v2
	v_mov_b32_e32 v53, v2
	v_mov_b32_e32 v54, v2
	v_mov_b32_e32 v55, v2
	v_mov_b32_e32 v56, v2
	v_mov_b32_e32 v57, v2
	v_mov_b32_e32 v58, v2
	v_mov_b32_e32 v59, v2
	v_mov_b32_e32 v60, v2
	v_mov_b32_e32 v61, v2
	v_mov_b32_e32 v62, v2
	v_mov_b32_e32 v63, v2
	v_mov_b32_e32 v64, v2
	v_mov_b32_e32 v65, v2
	v_mov_b32_e32 v66, v2
	v_mov_b32_e32 v67, v2
	v_mov_b32_e32 v68, v2
	v_mov_b32_e32 v69, v2
	v_mov_b32_e32 v70, v2
	v_mov_b32_e32 v71, v2
	v_mov_b32_e32 v72, v2
	v_mov_b32_e32 v73, v2
	v_mov_b32_e32 v74, v2
	v_mov_b32_e32 v75, v2
	v_mov_b32_e32 v76, v2
	v_mov_b32_e32 v77, v2
	v_mov_b32_e32 v78, v2
	v_mov_b32_e32 v79, v2
	v_mov_b32_e32 v80, v2
	v_mov_b32_e32 v81, v2
	v_mov_b32_e32 v82, v2
	v_mov_b32_e32 v83, v2
	v_mov_b32_e32 v84, v2
	v_mov_b32_e32 v85, v2
	v_mov_b32_e32 v86, v2
	v_mov_b32_e32 v87, v2
	v_mov_b32_e32 v88, v2
	v_mov_b32_e32 v89, v2
	v_mov_b32_e32 v90, v2
	v_mov_b32_e32 v91, v2
	v_mov_b32_e32 v92, v2
	v_mov_b32_e32 v93, v2
	v_mov_b32_e32 v94, v2
	v_mov_b32_e32 v95, v2
	v_mov_b32_e32 v96, v2
	v_mov_b32_e32 v97, v2
	v_mov_b32_e32 v98, v2
	v_mov_b32_e32 v99, v2
	v_mov_b32_e32 v100, v2
	v_mov_b32_e32 v101, v2
	v_mov_b32_e32 v102, v2
	v_mov_b32_e32 v103, v2
	v_mov_b32_e32 v104, v2
	v_mov_b32_e32 v105, v2
	v_mov_b32_e32 v106, v2
	v_mov_b32_e32 v107, v2
	v_mov_b32_e32 v108, v2
	v_mov_b32_e32 v109, v2
	v_mov_b32_e32 v110, v2
	v_mov_b32_e32 v111, v2
	v_mov_b32_e32 v112, v2
	v_mov_b32_e32 v113, v2
	v_mov_b32_e32 v114, v2
	v_mov_b32_e32 v115, v2
	v_mov_b32_e32 v116, v2
	v_mov_b32_e32 v117, v2
	v_mov_b32_e32 v118, v2
	v_mov_b32_e32 v119, v2
	v_mov_b32_e32 v120, v2
	v_mov_b32_e32 v121, v2
	v_mov_b32_e32 v122, v2
	v_mov_b32_e32 v123, v2
	v_mov_b32_e32 v124, v2
	v_mov_b32_e32 v125, v2
	v_mov_b32_e32 v126, v2
	v_mov_b32_e32 v127, v2
	v_mov_b32_e32 v128, v2
	v_mov_b32_e32 v129, v2

.LBB0_676:
	v_mov_b32_e32 v175, 0
	s_and_saveexec_b64 s[6:7], s[0:1]
	s_cbranch_execz .LBB0_680
	s_mov_b64 s[44:45], exec
	v_mbcnt_lo_u32_b32 v2, s44, 0
	v_mbcnt_hi_u32_b32 v2, s45, v2
	v_cmp_eq_u32_e32 vcc, 0, v2
	s_and_saveexec_b64 s[42:43], vcc
	s_cbranch_execz .LBB0_679
	s_bcnt1_i32_b64 s16, s[44:45]
	v_mov_b32_e32 v3, s16
	global_atomic_add v175, v147, v3, s[30:31] sc0
.LBB0_679:
	s_or_b64 exec, exec, s[42:43]
.LBB0_680:
	s_or_b64 exec, exec, s[6:7]
	s_lshl_b32 s16, s60, 6
	s_and_b32 s45, s16, 0xffffff00
	s_and_b32 s44, s60, 3
	v_or_b32_e32 v2, s45, v1
	s_or_b32 s6, s44, s57
	v_ashrrev_i32_e32 v3, 31, v2
	s_lshl_b32 s60, s6, 8
	v_lshlrev_b64 v[2:3], 11, v[2:3]
	v_readfirstlane_b32 s6, v182
	v_lshl_add_u64 v[130:131], v[176:177], 0, v[2:3]
	v_or_b32_e32 v2, s60, v1
	s_mov_b32 m0, s6
	v_readfirstlane_b32 s6, v161
	v_lshlrev_b32_e32 v2, 11, v2
	v_mov_b32_e32 v3, v147
	s_barrier
	global_load_lds_dwordx4 v[130:131], off
	v_lshl_add_u64 v[134:135], v[130:131], 0, s[18:19]
	s_mov_b32 m0, s6
	v_readfirstlane_b32 s6, v165
	v_lshl_add_u64 v[132:133], v[178:179], 0, v[2:3]
	global_load_lds_dwordx4 v[134:135], off
	s_mov_b32 m0, s6
	v_readfirstlane_b32 s6, v169
	global_load_lds_dwordx4 v[132:133], off
	v_lshl_add_u64 v[136:137], v[132:133], 0, s[18:19]
	s_mov_b32 m0, s6
	v_readfirstlane_b32 s6, v202
	global_load_lds_dwordx4 v[136:137], off
	v_lshl_add_u64 v[2:3], v[130:131], 0, 64
	s_mov_b32 m0, s6
	v_readfirstlane_b32 s6, v203
	global_load_lds_dwordx4 v[2:3], off
	v_lshl_add_u64 v[2:3], v[130:131], 0, s[20:21]
	s_mov_b32 m0, s6
	v_readfirstlane_b32 s6, v204
	global_load_lds_dwordx4 v[2:3], off
	v_lshl_add_u64 v[2:3], v[132:133], 0, 64
	s_mov_b32 m0, s6
	v_readfirstlane_b32 s6, v205
	global_load_lds_dwordx4 v[2:3], off
	v_lshl_add_u64 v[2:3], v[132:133], 0, s[20:21]
	s_mov_b32 m0, s6
	v_readfirstlane_b32 s6, v184
	global_load_lds_dwordx4 v[2:3], off
	v_lshl_add_u64 v[2:3], v[130:131], 0, s[22:23]
	s_mov_b32 m0, s6
	v_readfirstlane_b32 s6, v185
	global_load_lds_dwordx4 v[2:3], off
	v_lshl_add_u64 v[2:3], v[130:131], 0, s[24:25]
	s_mov_b32 m0, s6
	v_readfirstlane_b32 s6, v186
	global_load_lds_dwordx4 v[2:3], off
	v_lshl_add_u64 v[2:3], v[132:133], 0, s[22:23]
	s_mov_b32 m0, s6
	v_readfirstlane_b32 s6, v187
	global_load_lds_dwordx4 v[2:3], off
	v_lshl_add_u64 v[2:3], v[132:133], 0, s[24:25]
	s_mov_b32 m0, s6
	s_mov_b32 s7, 3
	global_load_lds_dwordx4 v[2:3], off
	v_mov_b32_e32 v2, 0
	s_mov_b32 s42, 0
	s_mov_b32 s6, 0
	v_mov_b32_e32 v3, v2
	v_mov_b32_e32 v4, v2
	v_mov_b32_e32 v5, v2
	v_mov_b32_e32 v6, v2
	v_mov_b32_e32 v7, v2
	v_mov_b32_e32 v8, v2
	v_mov_b32_e32 v9, v2
	v_mov_b32_e32 v10, v2
	v_mov_b32_e32 v11, v2
	v_mov_b32_e32 v12, v2
	v_mov_b32_e32 v13, v2
	v_mov_b32_e32 v14, v2
	v_mov_b32_e32 v15, v2
	v_mov_b32_e32 v16, v2
	v_mov_b32_e32 v17, v2
	v_mov_b32_e32 v18, v2
	v_mov_b32_e32 v19, v2
	v_mov_b32_e32 v20, v2
	v_mov_b32_e32 v21, v2
	v_mov_b32_e32 v22, v2
	v_mov_b32_e32 v23, v2
	v_mov_b32_e32 v24, v2
	v_mov_b32_e32 v25, v2
	v_mov_b32_e32 v26, v2
	v_mov_b32_e32 v27, v2
	v_mov_b32_e32 v28, v2
	v_mov_b32_e32 v29, v2
	v_mov_b32_e32 v30, v2
	v_mov_b32_e32 v31, v2
	v_mov_b32_e32 v32, v2
	v_mov_b32_e32 v33, v2
	v_mov_b32_e32 v34, v2
	v_mov_b32_e32 v35, v2
	v_mov_b32_e32 v36, v2
	v_mov_b32_e32 v37, v2
	v_mov_b32_e32 v38, v2
	v_mov_b32_e32 v39, v2
	v_mov_b32_e32 v40, v2
	v_mov_b32_e32 v41, v2
	v_mov_b32_e32 v42, v2
	v_mov_b32_e32 v43, v2
	v_mov_b32_e32 v44, v2
	v_mov_b32_e32 v45, v2
	v_mov_b32_e32 v46, v2
	v_mov_b32_e32 v47, v2
	v_mov_b32_e32 v48, v2
	v_mov_b32_e32 v49, v2
	v_mov_b32_e32 v50, v2
	v_mov_b32_e32 v51, v2
	v_mov_b32_e32 v52, v2
	v_mov_b32_e32 v53, v2
	v_mov_b32_e32 v54, v2
	v_mov_b32_e32 v55, v2
	v_mov_b32_e32 v56, v2
	v_mov_b32_e32 v57, v2
	v_mov_b32_e32 v58, v2
	v_mov_b32_e32 v59, v2
	v_mov_b32_e32 v60, v2
	v_mov_b32_e32 v61, v2
	v_mov_b32_e32 v62, v2
	v_mov_b32_e32 v63, v2
	v_mov_b32_e32 v64, v2
	v_mov_b32_e32 v65, v2
	v_mov_b32_e32 v66, v2
	v_mov_b32_e32 v67, v2
	v_mov_b32_e32 v68, v2
	v_mov_b32_e32 v69, v2
	v_mov_b32_e32 v70, v2
	v_mov_b32_e32 v71, v2
	v_mov_b32_e32 v72, v2
	v_mov_b32_e32 v73, v2
	v_mov_b32_e32 v74, v2
	v_mov_b32_e32 v75, v2
	v_mov_b32_e32 v76, v2
	v_mov_b32_e32 v77, v2
	v_mov_b32_e32 v78, v2
	v_mov_b32_e32 v79, v2
	v_mov_b32_e32 v80, v2
	v_mov_b32_e32 v81, v2
	v_mov_b32_e32 v82, v2
	v_mov_b32_e32 v83, v2
	v_mov_b32_e32 v84, v2
	v_mov_b32_e32 v85, v2
	v_mov_b32_e32 v86, v2
	v_mov_b32_e32 v87, v2
	v_mov_b32_e32 v88, v2
	v_mov_b32_e32 v89, v2
	s_waitcnt vmcnt(0)
	v_mov_b32_e32 v90, v2
	v_mov_b32_e32 v91, v2
	v_mov_b32_e32 v92, v2
	v_mov_b32_e32 v93, v2
	v_mov_b32_e32 v94, v2
	v_mov_b32_e32 v95, v2
	v_mov_b32_e32 v96, v2
	v_mov_b32_e32 v97, v2
	v_mov_b32_e32 v98, v2
	v_mov_b32_e32 v99, v2
	v_mov_b32_e32 v100, v2
	v_mov_b32_e32 v101, v2
	v_mov_b32_e32 v102, v2
	v_mov_b32_e32 v103, v2
	v_mov_b32_e32 v104, v2
	v_mov_b32_e32 v105, v2
	v_mov_b32_e32 v106, v2
	v_mov_b32_e32 v107, v2
	v_mov_b32_e32 v108, v2
	v_mov_b32_e32 v109, v2
	v_mov_b32_e32 v110, v2
	v_mov_b32_e32 v111, v2
	v_mov_b32_e32 v112, v2
	v_mov_b32_e32 v113, v2
	v_mov_b32_e32 v114, v2
	v_mov_b32_e32 v115, v2
	v_mov_b32_e32 v116, v2
	v_mov_b32_e32 v117, v2
	v_mov_b32_e32 v118, v2
	v_mov_b32_e32 v119, v2
	v_mov_b32_e32 v120, v2
	v_mov_b32_e32 v121, v2
	v_mov_b32_e32 v122, v2
	v_mov_b32_e32 v123, v2
	v_mov_b32_e32 v124, v2
	v_mov_b32_e32 v125, v2
	v_mov_b32_e32 v126, v2
	v_mov_b32_e32 v127, v2
	v_mov_b32_e32 v128, v2
	v_mov_b32_e32 v129, v2

.LBB0_1132:
	v_mov_b32_e32 v155, 0
	s_and_saveexec_b64 s[12:13], s[0:1]
	s_cbranch_execz .LBB0_1136
	s_mov_b64 s[16:17], exec
	v_mbcnt_lo_u32_b32 v0, s16, 0
	v_mbcnt_hi_u32_b32 v0, s17, v0
	v_cmp_eq_u32_e32 vcc, 0, v0
	s_and_saveexec_b64 s[14:15], vcc
	s_cbranch_execz .LBB0_1135
	s_bcnt1_i32_b64 s16, s[16:17]
	v_mov_b32_e32 v1, s16
	global_atomic_add v155, v121, v1, s[10:11] sc0
.LBB0_1135:
	s_or_b64 exec, exec, s[14:15]
.LBB0_1136:
	s_or_b64 exec, exec, s[12:13]
	s_add_i32 s12, s35, s34
	s_lshl_b32 s13, s12, 5
	s_and_b32 s14, s13, 0xffffff00
	s_add_i32 s14, s14, 0x8000
	v_add_u32_e32 v0, s14, v136
	v_ashrrev_i32_e32 v1, 31, v0
	v_lshlrev_b64 v[0:1], 12, v[0:1]
	v_lshl_add_u64 v[0:1], v[122:123], 0, v[0:1]
	s_lshl_b32 s12, s12, 7
	v_add_co_u32_e32 v4, vcc, s21, v0
	s_and_b32 s15, s12, 0x380
	s_nop 0
	v_addc_co_u32_e32 v5, vcc, 0, v1, vcc
	v_or_b32_e32 v2, s15, v135
	global_load_dwordx4 v[36:39], v[4:5], off offset:-4096
	global_load_dwordx4 v[40:43], v[4:5], off
	v_add_co_u32_e32 v4, vcc, s22, v0
	v_lshlrev_b32_e32 v120, 12, v2
	s_nop 0
	v_addc_co_u32_e32 v5, vcc, 0, v1, vcc
	v_lshl_add_u64 v[2:3], v[124:125], 0, v[120:121]
	global_load_dwordx4 v[44:47], v[4:5], off
	global_load_dwordx4 v[48:51], v[0:1], off
	global_load_dwordx4 v[52:55], v[2:3], off
	v_add_co_u32_e32 v0, vcc, s23, v2
	s_lshl_b32 s17, s35, 5
	s_nop 0
	v_addc_co_u32_e32 v1, vcc, 0, v3, vcc
	global_load_dwordx4 v[56:59], v[0:1], off
	s_lshl_b32 s35, s35, 7
	s_add_i32 s17, s31, s17
	s_add_i32 s35, s33, s35
	s_and_b32 s17, s17, 0xffffff00
	s_lshl_b32 s35, s35, 11
	v_add_u32_e32 v60, s17, v150
	s_and_b32 s17, s35, 0x1c0000
	v_ashrrev_i32_e32 v61, 31, v60
	v_mov_b32_e32 v0, 0
	v_lshlrev_b64 v[60:61], 12, v[60:61]
	v_add_u32_e32 v120, s17, v151
	s_mov_b32 s16, 0
	s_mov_b64 s[12:13], 0
	v_mov_b32_e32 v1, v0
	v_mov_b32_e32 v2, v0
	v_mov_b32_e32 v3, v0
	v_mov_b32_e32 v4, v0
	v_mov_b32_e32 v5, v0
	v_mov_b32_e32 v6, v0
	v_mov_b32_e32 v7, v0
	v_mov_b32_e32 v8, v0
	v_mov_b32_e32 v9, v0
	v_mov_b32_e32 v10, v0
	v_mov_b32_e32 v11, v0
	v_mov_b32_e32 v12, v0
	v_mov_b32_e32 v13, v0
	v_mov_b32_e32 v14, v0
	v_mov_b32_e32 v15, v0
	v_mov_b32_e32 v16, v0
	v_mov_b32_e32 v17, v0
	v_mov_b32_e32 v18, v0
	v_mov_b32_e32 v19, v0
	v_mov_b32_e32 v20, v0
	v_mov_b32_e32 v21, v0
	s_waitcnt vmcnt(7)
	v_mov_b32_e32 v22, v0
	v_mov_b32_e32 v23, v0
	v_mov_b32_e32 v24, v0
	v_mov_b32_e32 v25, v0
	v_mov_b32_e32 v26, v0
	v_mov_b32_e32 v27, v0
	v_mov_b32_e32 v28, v0
	v_mov_b32_e32 v29, v0
	v_mov_b32_e32 v30, v0
	v_mov_b32_e32 v31, v0
	v_mov_b32_e32 v32, v0
	v_mov_b32_e32 v33, v0
	s_waitcnt vmcnt(6)
	v_mov_b32_e32 v34, v0
	v_lshl_add_u64 v[64:65], v[126:127], 0, v[60:61]
	v_lshl_add_u64 v[66:67], v[120:121], 1, v[126:127]
	v_mov_b32_e32 v35, v0
	v_mov_b32_e32 v60, v0
	v_mov_b32_e32 v61, v0
	v_mov_b32_e32 v62, v0
	v_mov_b32_e32 v63, v0
	s_waitcnt vmcnt(2)
	ds_write_b128 v140, v[48:51]
	ds_write_b128 v140, v[36:39] offset:128
	ds_write_b128 v141, v[40:43]
	ds_write_b128 v143, v[44:47]
	s_waitcnt vmcnt(1)
	ds_write_b128 v139, v[52:55] offset:32768
	s_waitcnt vmcnt(0)
	ds_write_b128 v139, v[56:59] offset:40960
	v_mov_b32_e32 v36, v0
	v_mov_b32_e32 v37, v0
	v_mov_b32_e32 v38, v0
	v_mov_b32_e32 v39, v0
	v_mov_b32_e32 v40, v0
	v_mov_b32_e32 v41, v0
	v_mov_b32_e32 v42, v0
	v_mov_b32_e32 v43, v0
	v_mov_b32_e32 v44, v0
	v_mov_b32_e32 v45, v0
	v_mov_b32_e32 v46, v0
	v_mov_b32_e32 v47, v0
	v_mov_b32_e32 v48, v0
	v_mov_b32_e32 v49, v0
	v_mov_b32_e32 v50, v0
	v_mov_b32_e32 v51, v0
	v_mov_b32_e32 v52, v0
	v_mov_b32_e32 v53, v0
	v_mov_b32_e32 v54, v0
	v_mov_b32_e32 v55, v0
	v_mov_b32_e32 v56, v0
	v_mov_b32_e32 v57, v0
	v_mov_b32_e32 v58, v0
	v_mov_b32_e32 v59, v0
	s_waitcnt lgkmcnt(0)
	s_barrier

.LBB0_1149:
	v_mov_b32_e32 v162, 0
	s_and_saveexec_b64 s[20:21], s[0:1]
	s_cbranch_execz .LBB0_1153
	s_mov_b64 s[24:25], exec
	v_mbcnt_lo_u32_b32 v0, s24, 0
	v_mbcnt_hi_u32_b32 v0, s25, v0
	v_cmp_eq_u32_e32 vcc, 0, v0
	s_and_saveexec_b64 s[22:23], vcc
	s_cbranch_execz .LBB0_1152
	s_bcnt1_i32_b64 s4, s[24:25]
	v_mov_b32_e32 v1, s4
	global_atomic_add v162, v129, v1, s[18:19] sc0
.LBB0_1152:
	s_or_b64 exec, exec, s[22:23]
.LBB0_1153:
	s_or_b64 exec, exec, s[20:21]
	s_lshl_b32 s4, s31, 6
	s_add_i32 s4, s4, s30
	s_and_b32 s20, s4, 0xffffff00
	v_or_b32_e32 v0, s20, v143
	s_lshl_b32 s4, s31, 8
	v_ashrrev_i32_e32 v1, 31, v0
	s_and_b32 s21, s4, 0x300
	v_lshlrev_b64 v[0:1], 12, v[0:1]
	v_readfirstlane_b32 s4, v144
	v_lshl_add_u64 v[134:135], v[130:131], 0, v[0:1]
	v_or_b32_e32 v0, s21, v143
	s_mov_b32 m0, s4
	v_readfirstlane_b32 s4, v155
	v_lshlrev_b32_e32 v128, 12, v0
	s_barrier
	global_load_lds_dwordx4 v[134:135], off
	v_lshl_add_u64 v[138:139], v[134:135], 0, s[6:7]
	s_mov_b32 m0, s4
	v_readfirstlane_b32 s4, v156
	v_lshl_add_u64 v[136:137], v[132:133], 0, v[128:129]
	global_load_lds_dwordx4 v[138:139], off
	s_mov_b32 m0, s4
	v_readfirstlane_b32 s4, v157
	global_load_lds_dwordx4 v[136:137], off
	v_lshl_add_u64 v[140:141], v[136:137], 0, s[6:7]
	s_mov_b32 m0, s4
	v_readfirstlane_b32 s4, v158
	global_load_lds_dwordx4 v[140:141], off
	v_lshl_add_u64 v[0:1], v[134:135], 0, 64
	s_mov_b32 m0, s4
	v_readfirstlane_b32 s4, v159
	global_load_lds_dwordx4 v[0:1], off
	v_lshl_add_u64 v[0:1], v[134:135], 0, s[8:9]
	s_mov_b32 m0, s4
	v_readfirstlane_b32 s4, v160
	global_load_lds_dwordx4 v[0:1], off
	v_lshl_add_u64 v[0:1], v[136:137], 0, 64
	s_mov_b32 m0, s4
	v_readfirstlane_b32 s4, v161
	global_load_lds_dwordx4 v[0:1], off
	v_lshl_add_u64 v[0:1], v[136:137], 0, s[8:9]
	s_mov_b32 m0, s4
	v_readfirstlane_b32 s4, v146
	global_load_lds_dwordx4 v[0:1], off
	v_lshl_add_u64 v[0:1], v[134:135], 0, s[10:11]
	s_mov_b32 m0, s4
	v_readfirstlane_b32 s4, v147
	global_load_lds_dwordx4 v[0:1], off
	v_lshl_add_u64 v[0:1], v[134:135], 0, s[12:13]
	s_mov_b32 m0, s4
	v_readfirstlane_b32 s4, v148
	global_load_lds_dwordx4 v[0:1], off
	v_lshl_add_u64 v[0:1], v[136:137], 0, s[10:11]
	s_mov_b32 m0, s4
	v_readfirstlane_b32 s4, v149
	global_load_lds_dwordx4 v[0:1], off
	v_lshl_add_u64 v[0:1], v[136:137], 0, s[12:13]
	s_mov_b32 m0, s4
	s_mov_b32 s23, 3
	global_load_lds_dwordx4 v[0:1], off
	v_mov_b32_e32 v0, 0
	s_mov_b32 s24, 0
	s_mov_b32 s22, 0
	v_mov_b32_e32 v1, v0
	v_mov_b32_e32 v2, v0
	v_mov_b32_e32 v3, v0
	v_mov_b32_e32 v4, v0
	v_mov_b32_e32 v5, v0
	v_mov_b32_e32 v6, v0
	v_mov_b32_e32 v7, v0
	v_mov_b32_e32 v8, v0
	v_mov_b32_e32 v9, v0
	v_mov_b32_e32 v10, v0
	v_mov_b32_e32 v11, v0
	v_mov_b32_e32 v12, v0
	v_mov_b32_e32 v13, v0
	v_mov_b32_e32 v14, v0
	v_mov_b32_e32 v15, v0
	v_mov_b32_e32 v16, v0
	v_mov_b32_e32 v17, v0
	v_mov_b32_e32 v18, v0
	v_mov_b32_e32 v19, v0
	v_mov_b32_e32 v20, v0
	v_mov_b32_e32 v21, v0
	s_waitcnt vmcnt(0)
	v_mov_b32_e32 v22, v0
	v_mov_b32_e32 v23, v0
	v_mov_b32_e32 v24, v0
	v_mov_b32_e32 v25, v0
	v_mov_b32_e32 v26, v0
	v_mov_b32_e32 v27, v0
	v_mov_b32_e32 v28, v0
	v_mov_b32_e32 v29, v0
	v_mov_b32_e32 v30, v0
	v_mov_b32_e32 v31, v0
	v_mov_b32_e32 v32, v0
	v_mov_b32_e32 v33, v0
	v_mov_b32_e32 v34, v0
	v_mov_b32_e32 v35, v0
	v_mov_b32_e32 v36, v0
	v_mov_b32_e32 v37, v0
	v_mov_b32_e32 v38, v0
	v_mov_b32_e32 v39, v0
	v_mov_b32_e32 v40, v0
	v_mov_b32_e32 v41, v0
	v_mov_b32_e32 v42, v0
	v_mov_b32_e32 v43, v0
	v_mov_b32_e32 v44, v0
	v_mov_b32_e32 v45, v0
	v_mov_b32_e32 v46, v0
	v_mov_b32_e32 v47, v0
	v_mov_b32_e32 v48, v0
	v_mov_b32_e32 v49, v0
	v_mov_b32_e32 v50, v0
	v_mov_b32_e32 v51, v0
	v_mov_b32_e32 v52, v0
	v_mov_b32_e32 v53, v0
	v_mov_b32_e32 v54, v0
	v_mov_b32_e32 v55, v0
	v_mov_b32_e32 v56, v0
	v_mov_b32_e32 v57, v0
	v_mov_b32_e32 v58, v0
	v_mov_b32_e32 v59, v0
	v_mov_b32_e32 v60, v0
	v_mov_b32_e32 v61, v0
	v_mov_b32_e32 v62, v0
	v_mov_b32_e32 v63, v0
	v_mov_b32_e32 v64, v0
	v_mov_b32_e32 v65, v0
	v_mov_b32_e32 v66, v0
	v_mov_b32_e32 v67, v0
	v_mov_b32_e32 v68, v0
	v_mov_b32_e32 v69, v0
	v_mov_b32_e32 v70, v0
	v_mov_b32_e32 v71, v0
	v_mov_b32_e32 v72, v0
	v_mov_b32_e32 v73, v0
	v_mov_b32_e32 v74, v0
	v_mov_b32_e32 v75, v0
	v_mov_b32_e32 v76, v0
	v_mov_b32_e32 v77, v0
	v_mov_b32_e32 v78, v0
	v_mov_b32_e32 v79, v0
	v_mov_b32_e32 v80, v0
	v_mov_b32_e32 v81, v0
	v_mov_b32_e32 v82, v0
	v_mov_b32_e32 v83, v0
	v_mov_b32_e32 v84, v0
	v_mov_b32_e32 v85, v0
	v_mov_b32_e32 v86, v0
	v_mov_b32_e32 v87, v0
	v_mov_b32_e32 v88, v0
	v_mov_b32_e32 v89, v0
	v_mov_b32_e32 v90, v0
	v_mov_b32_e32 v91, v0
	v_mov_b32_e32 v92, v0
	v_mov_b32_e32 v93, v0
	v_mov_b32_e32 v94, v0
	v_mov_b32_e32 v95, v0
	v_mov_b32_e32 v96, v0
	v_mov_b32_e32 v97, v0
	v_mov_b32_e32 v98, v0
	v_mov_b32_e32 v99, v0
	v_mov_b32_e32 v100, v0
	v_mov_b32_e32 v101, v0
	v_mov_b32_e32 v102, v0
	v_mov_b32_e32 v103, v0
	v_mov_b32_e32 v104, v0
	v_mov_b32_e32 v105, v0
	v_mov_b32_e32 v106, v0
	v_mov_b32_e32 v107, v0
	v_mov_b32_e32 v108, v0
	v_mov_b32_e32 v109, v0
	v_mov_b32_e32 v110, v0
	v_mov_b32_e32 v111, v0
	v_mov_b32_e32 v112, v0
	v_mov_b32_e32 v113, v0
	v_mov_b32_e32 v114, v0
	v_mov_b32_e32 v115, v0
	v_mov_b32_e32 v116, v0
	v_mov_b32_e32 v117, v0
	v_mov_b32_e32 v118, v0
	v_mov_b32_e32 v119, v0
	v_mov_b32_e32 v120, v0
	v_mov_b32_e32 v121, v0
	v_mov_b32_e32 v122, v0
	v_mov_b32_e32 v123, v0
	v_mov_b32_e32 v124, v0
	v_mov_b32_e32 v125, v0
	v_mov_b32_e32 v126, v0
	v_mov_b32_e32 v127, v0
